# p0a: odd workgroups run the x->bf16 streaming section before the pool-fold and G-matrix sections so latency-bound and bandwidth-bound work overlap across the chip
# speedup vs baseline: 1.0048x; 1.0048x over previous
_ZN2mk6mk_fwdENS_4ArgsE:
	s_and_b32 s100, s2, 1
	s_mov_b64 s[4:5], s[0:1]
	s_load_dwordx2 s[60:61], s[0:1], 0x130
	s_load_dword s3, s[0:1], 0x138
	s_load_dwordx2 s[62:63], s[4:5], 0x120
	s_add_u32 s6, s0, 0x130
	v_writelane_b32 v251, s0, 0
	v_and_b32_e32 v200, 0x3ff, v0
	s_addc_u32 s7, s1, 0
	v_writelane_b32 v251, s1, 1
	v_readfirstlane_b32 s4, v200
	v_cmp_gt_u32_e32 vcc, 16, v200
	s_and_saveexec_b64 s[0:1], vcc
	v_lshl_add_u32 v1, v200, 2, 0
	v_add_u32_e32 v1, 0x24000, v1
	v_mov_b32_e32 v2, 0
	ds_write_b32 v1, v2
	s_or_b64 exec, exec, s[0:1]
	s_waitcnt lgkmcnt(0)
	s_barrier
	s_getreg_b32 s0, hwreg(HW_REG_XCC_ID, 0, 4)
	s_and_b32 s5, s0, 15
	v_cmp_eq_u32_e64 s[96:97], 0, v200
	s_and_saveexec_b64 s[0:1], s[96:97]
	s_cbranch_execz .LBB7_5
	s_mov_b64 s[8:9], exec
	v_mbcnt_lo_u32_b32 v1, s8, 0
	v_mbcnt_hi_u32_b32 v1, s9, v1
	v_cmp_eq_u32_e32 vcc, 0, v1
	s_and_b64 s[10:11], exec, vcc
	s_mov_b64 exec, s[10:11]
	s_cbranch_execz .LBB7_5
	s_lshl_b32 s10, s5, 8
	s_bcnt1_i32_b64 s8, s[8:9]
	v_mov_b32_e32 v1, s10
	v_mov_b32_e32 v2, s8
	global_atomic_add v1, v2, s[62:63] offset:1024

.LBB7_169:
	s_cmp_eq_u32 s100, 1
	s_cbranch_scc0 .Lp0_P
	s_mov_b32 s100, 2
	s_waitcnt vmcnt(0)
	s_mov_b64 s[24:25], exec
	s_branch .LBB7_217

.LBB7_217:
	s_or_b64 exec, exec, s[24:25]
	s_cmp_eq_u32 s100, 3
	s_cbranch_scc1 .Lp0_K
	s_cmp_lt_i32 s70, 0x9000
	s_cbranch_scc0 .LBB7_239
	v_lshlrev_b32_e32 v32, 2, v201
	v_mov_b32_e32 v33, 0
	v_lshl_add_u64 v[0:1], s[22:23], 0, v[32:33]
	s_mov_b64 s[8:9], 0x1ce80000
	v_lshl_add_u64 v[34:35], v[0:1], 0, s[8:9]
	v_mbcnt_lo_u32_b32 v0, -1, 0
	v_mbcnt_hi_u32_b32 v37, -1, v0
	s_add_u32 s16, s22, 0x1cd80000
	v_and_b32_e32 v0, 64, v37
	v_cmp_eq_u32_e64 s[6:7], 0, v201
	s_addc_u32 s17, s23, 0
	v_lshlrev_b32_e32 v36, 4, v201
	s_mov_b32 s18, 0xa380000
	v_lshlrev_b32_e32 v32, 1, v32
	s_waitcnt vmcnt(7)
	v_add_u32_e32 v38, 64, v0
	s_waitcnt vmcnt(6)
	v_xor_b32_e32 v39, 1, v37
	s_waitcnt vmcnt(5)
	v_xor_b32_e32 v40, 2, v37
	s_waitcnt vmcnt(4)
	v_mov_b32_e32 v41, 0x358637bd
	s_mov_b32 s19, 0x800000
	v_xor_b32_e32 v42, 4, v37
	v_xor_b32_e32 v43, 8, v37
	s_mov_b32 s10, s70
	s_branch .LBB7_221

.LBB7_239:
	s_cmp_eq_u32 s100, 2
	s_cbranch_scc0 .Lp0_K
	s_mov_b32 s100, 3
	s_waitcnt vmcnt(0)
	s_branch .Lp0_P
